# baseline (speedup 1.0000x reference)
;     ...
;   for (int i = 0; i < MS / 2; ++i) ap[i] = arow(lrow + 64 * i) + lc;
;   const long brs = (b_rs < 0) ? ldb : b_rs;
;   const u16* bp0 = ((b_rs < 0) ? Bt + (long)n0 * ldb : Bt) + (long)lrow * brs + lc;
;   const u16* bp1 = bp0 + 64 * brs;
;   asm volatile("" : "+v"(bp0), "+v"(bp1));
;   const int nk = nk64 * 2;
;   const int wbase = __builtin_amdgcn_readfirstlane(wid) * 1024;
;   const int rg = (l15 >> 2) & 3;
;   const int gr = (rg == 0) ? 0 : (rg == 1) ? 2 : (rg == 2) ? 3 : 1;
;   const int aoff_r = (wm * (MS * 16) + l15) * 64 + ((quad ^ gr) << 4);
;   const int boff_r = A_BYTES + (wn * 64 + l15) * 64 + ((quad ^ gr) << 4);
;     ...
;   if (!prefetched) {
;     ISSUE(0)
;     ISSUE(1)
;     if (NST == 4) ISSUE(2)
;   }
; template <int MS>
; DEV void zero_acc(f32x4 (&acc)[MS][4]) {
; #pragma unroll
;   for (int a = 0; a < MS; ++a)
; #pragma unroll
;     for (int b = 0; b < 4; ++b) acc[a][b] = f32x4{0.f, 0.f, 0.f, 0.f};
.LBB0_1413:
	s_or_b64 exec, exec, s[4:5]
	s_lshl_b32 s2, s2, 3
	v_readlane_b32 s4, v252, 11
	s_add_i32 s2, s2, s4
	s_and_b32 s4, s20, 7
	s_or_b32 s2, s2, s4
	s_lshl_b32 s16, s2, 8
	s_ashr_i32 s17, s16, 31
	s_lshl_b64 s[4:5], s[16:17], 11
	s_add_u32 s4, s42, s4
	s_addc_u32 s5, s43, s5
	v_lshlrev_b32_e32 v0, 1, v8
	v_lshl_add_u64 v[12:13], s[4:5], 0, v[0:1]
	v_lshlrev_b64 v[6:7], 6, v[6:7]
	s_mov_b64 s[4:5], 0x1000
	v_lshl_add_u64 v[192:193], v[6:7], 0, s[4:5]
	s_mov_b64 s[4:5], 0x3000
	v_lshl_add_u64 v[194:195], v[6:7], 0, s[76:77]
	v_lshl_add_u64 v[196:197], v[6:7], 0, s[4:5]
	s_lshl_b32 s11, s11, 10
	v_lshl_add_u64 v[198:199], v[12:13], 0, v[190:191]
	v_lshl_add_u64 v[200:201], v[12:13], 0, v[192:193]
	v_lshl_add_u64 v[202:203], v[12:13], 0, v[194:195]
	s_cmp_lg_u32 s20, s46
	v_lshl_add_u64 v[204:205], v[12:13], 0, v[196:197]
	s_cbranch_scc1 .LBB0_1415
	s_mov_b32 m0, s11
	s_mov_b64 s[4:5], 0x4000
	global_load_lds_dwordx4 v[198:199], off
	s_add_i32 m0, s11, 0x1000
	v_lshl_add_u64 v[6:7], v[198:199], 0, s[4:5]
	global_load_lds_dwordx4 v[200:201], off
	s_add_i32 m0, s11, 0x2000
	s_nop 0
	global_load_lds_dwordx4 v[202:203], off
	s_add_i32 m0, s11, 0x3000
	s_nop 0
	global_load_lds_dwordx4 v[204:205], off
	s_add_i32 m0, s11, 0x4000
	s_nop 0
	global_load_lds_dwordx4 v[2:3], off
	s_add_i32 m0, s11, 0x5000
	s_nop 0
	global_load_lds_dwordx4 v[4:5], off
	s_add_i32 m0, s11, 0x6000
	s_nop 0
	global_load_lds_dwordx4 v[6:7], off
	v_lshl_add_u64 v[6:7], v[200:201], 0, s[4:5]
	s_add_i32 m0, s11, 0x7000
	s_nop 0
	global_load_lds_dwordx4 v[6:7], off
	v_lshl_add_u64 v[6:7], v[202:203], 0, s[4:5]
	s_add_i32 m0, s11, 0x8000
	s_nop 0
	global_load_lds_dwordx4 v[6:7], off
	v_lshl_add_u64 v[6:7], v[204:205], 0, s[4:5]
	s_add_i32 m0, s11, 0x9000
	s_nop 0
	global_load_lds_dwordx4 v[6:7], off
	v_lshl_add_u64 v[6:7], v[2:3], 0, s[76:77]
	s_add_i32 m0, s11, 0xa000
	s_nop 0
	global_load_lds_dwordx4 v[6:7], off
	v_lshl_add_u64 v[6:7], v[4:5], 0, s[76:77]
	s_add_i32 m0, s11, 0xb000
	s_nop 0
	global_load_lds_dwordx4 v[6:7], off
	s_waitcnt vmcnt(0)
.LBB0_1415:
	v_lshlrev_b32_e32 v6, 6, v9
	s_mov_b64 s[4:5], 0x4000
	v_mov_b32_e32 v30, 0
	v_and_b32_e32 v241, 0xffffe3c0, v6
	v_bitop3_b32 v242, v10, v9, 48 bitop3:0x78
	v_and_b32_e32 v243, 0x13c0, v6
	v_lshl_add_u64 v[206:207], v[4:5], 0, s[4:5]
	v_lshl_add_u64 v[208:209], v[2:3], 0, s[4:5]
	s_mov_b64 s[4:5], 0
	s_mov_b32 s17, 2
	s_mov_b32 s18, 0
	s_mov_b32 s19, 0
	v_mov_b32_e32 v31, v30
	v_mov_b32_e32 v32, v30
	v_mov_b32_e32 v33, v30
	v_mov_b32_e32 v42, v30
	v_mov_b32_e32 v43, v30
	v_mov_b32_e32 v44, v30
	v_mov_b32_e32 v45, v30
	v_mov_b32_e32 v34, v30
	v_mov_b32_e32 v35, v30
	v_mov_b32_e32 v36, v30
	v_mov_b32_e32 v37, v30
	v_mov_b32_e32 v2, v30
	v_mov_b32_e32 v3, v30
	v_mov_b32_e32 v4, v30
	v_mov_b32_e32 v5, v30
	v_mov_b32_e32 v46, v30
	v_mov_b32_e32 v47, v30
	v_mov_b32_e32 v48, v30
	v_mov_b32_e32 v49, v30
	v_mov_b32_e32 v54, v30
	v_mov_b32_e32 v55, v30
	v_mov_b32_e32 v56, v30
	v_mov_b32_e32 v57, v30
	v_mov_b32_e32 v50, v30
	v_mov_b32_e32 v51, v30
	v_mov_b32_e32 v52, v30
	v_mov_b32_e32 v53, v30
	v_mov_b32_e32 v6, v30
	v_mov_b32_e32 v7, v30
	v_mov_b32_e32 v8, v30
	v_mov_b32_e32 v9, v30
	v_mov_b32_e32 v58, v30
	v_mov_b32_e32 v59, v30
	v_mov_b32_e32 v60, v30
	v_mov_b32_e32 v61, v30
	v_mov_b32_e32 v66, v30
	v_mov_b32_e32 v67, v30
	v_mov_b32_e32 v68, v30
	v_mov_b32_e32 v69, v30
	v_mov_b32_e32 v62, v30
	v_mov_b32_e32 v63, v30
	v_mov_b32_e32 v64, v30
	v_mov_b32_e32 v65, v30
	v_mov_b32_e32 v10, v30
	v_mov_b32_e32 v11, v30
	v_mov_b32_e32 v12, v30
	v_mov_b32_e32 v13, v30
	v_mov_b32_e32 v70, v30
	v_mov_b32_e32 v71, v30
	v_mov_b32_e32 v72, v30
	v_mov_b32_e32 v73, v30
	v_mov_b32_e32 v78, v30
	v_mov_b32_e32 v79, v30
	v_mov_b32_e32 v80, v30
	v_mov_b32_e32 v81, v30
	v_mov_b32_e32 v74, v30
	v_mov_b32_e32 v75, v30
	v_mov_b32_e32 v76, v30
	v_mov_b32_e32 v77, v30
	v_mov_b32_e32 v14, v30
	v_mov_b32_e32 v15, v30
	v_mov_b32_e32 v16, v30
	v_mov_b32_e32 v17, v30
	v_mov_b32_e32 v82, v30
	v_mov_b32_e32 v83, v30
	v_mov_b32_e32 v84, v30
	v_mov_b32_e32 v85, v30
	v_mov_b32_e32 v90, v30
	v_mov_b32_e32 v91, v30
	v_mov_b32_e32 v92, v30
	v_mov_b32_e32 v93, v30
	v_mov_b32_e32 v86, v30
	v_mov_b32_e32 v87, v30
	v_mov_b32_e32 v88, v30
	v_mov_b32_e32 v89, v30
	v_mov_b32_e32 v18, v30
	v_mov_b32_e32 v19, v30
	v_mov_b32_e32 v20, v30
	v_mov_b32_e32 v21, v30
	v_mov_b32_e32 v94, v30
	v_mov_b32_e32 v95, v30
	v_mov_b32_e32 v96, v30
	v_mov_b32_e32 v97, v30
	v_mov_b32_e32 v102, v30
	v_mov_b32_e32 v103, v30
	v_mov_b32_e32 v104, v30
	v_mov_b32_e32 v105, v30
	v_mov_b32_e32 v98, v30
	v_mov_b32_e32 v99, v30
	v_mov_b32_e32 v100, v30
	v_mov_b32_e32 v101, v30
	v_mov_b32_e32 v22, v30
	v_mov_b32_e32 v23, v30
	v_mov_b32_e32 v24, v30
	v_mov_b32_e32 v25, v30
	v_mov_b32_e32 v106, v30
	v_mov_b32_e32 v107, v30
	v_mov_b32_e32 v108, v30
	v_mov_b32_e32 v109, v30
	v_mov_b32_e32 v114, v30
	v_mov_b32_e32 v115, v30
	v_mov_b32_e32 v116, v30
	v_mov_b32_e32 v117, v30
	v_mov_b32_e32 v110, v30
	v_mov_b32_e32 v111, v30
	v_mov_b32_e32 v112, v30
	v_mov_b32_e32 v113, v30
	v_mov_b32_e32 v26, v30
	v_mov_b32_e32 v27, v30
	v_mov_b32_e32 v28, v30
	v_mov_b32_e32 v29, v30
	v_mov_b32_e32 v118, v30
	v_mov_b32_e32 v119, v30
	v_mov_b32_e32 v120, v30
	v_mov_b32_e32 v121, v30
	v_mov_b32_e32 v126, v30
	v_mov_b32_e32 v127, v30
	v_mov_b32_e32 v128, v30
	v_mov_b32_e32 v129, v30
	v_mov_b32_e32 v122, v30
	v_mov_b32_e32 v123, v30
	v_mov_b32_e32 v124, v30
	v_mov_b32_e32 v125, v30
	v_mov_b32_e32 v38, v30
	v_mov_b32_e32 v39, v30
	v_mov_b32_e32 v40, v30
	v_mov_b32_e32 v41, v30
	s_branch .LBB0_1417

;     ...
;   for (int kt = 0; kt < nk; ++kt) {
;     if (NST == 4 && kt + 2 < nk) asm volatile("s_waitcnt vmcnt(%0)" ::"n"(2 * NLD) : "memory");
;     else if (kt + 1 < nk) asm volatile("s_waitcnt vmcnt(%0)" ::"n"(NLD) : "memory");
;     else asm volatile("s_waitcnt vmcnt(0)" ::: "memory");
;     __builtin_amdgcn_s_barrier();
;     const char* st = smem + (kt % NST) * STAGE;
;     bf16x8 af[MS], bfr[4];
; #pragma unroll
;     for (int ms = 0; ms < MS; ++ms) af[ms] = *(const bf16x8*)(st + aoff_r + ms * 1024);
; #pragma unroll
;     for (int ns = 0; ns < 4; ++ns) bfr[ns] = *(const bf16x8*)(st + boff_r + ns * 1024);
;     asm volatile("" ::: "memory");
;     if (kt + NST - 1 < nk) ISSUE(kt + NST - 1)
;     __builtin_amdgcn_s_setprio(1);
; #pragma unroll
;     for (int ms = 0; ms < MS; ++ms)
; #pragma unroll
;       for (int ns = 0; ns < 4; ++ns) acc[ms][ns] = __builtin_amdgcn_mfma_f32_16x16x32_bf16(af[ms], bfr[ns], acc[ms][ns], 0, 0, 0);
;     __builtin_amdgcn_s_setprio(0);
.LBB0_1419:
	s_andn2_b64 vcc, exec, s[12:13]
	s_cbranch_vccnz .LBB0_1421
	s_cmp_lt_u32 s2, 2
	s_cbranch_scc1 .Ldrain_early_wi
	s_waitcnt vmcnt(6)
	s_branch .LBB0_1421
.Ldrain_early_wi:
	s_waitcnt vmcnt(63)
.LBB0_1421:
	s_mul_hi_u32 s12, s19, 0xaaaaaaab
	s_lshr_b32 s12, s12, 1
	s_mul_i32 s12, s12, 0x12000
	v_subrev_u32_e32 v130, s12, v241
	v_add_u32_e32 v139, s18, v242
	v_add_u32_e32 v130, v139, v130
	v_subrev_u32_e32 v138, s12, v243
	v_add_u32_e32 v150, v139, v138
	s_barrier
	ds_read_b128 v[138:141], v150 offset:16384
	ds_read_b128 v[142:145], v150 offset:17408
	ds_read_b128 v[146:149], v150 offset:18432
	ds_read_b128 v[150:153], v150 offset:19456
	ds_read_b128 v[174:177], v130
	ds_read_b128 v[170:173], v130 offset:1024
	ds_read_b128 v[166:169], v130 offset:2048
	ds_read_b128 v[162:165], v130 offset:3072
	ds_read_b128 v[158:161], v130 offset:4096
	ds_read_b128 v[154:157], v130 offset:5120
	ds_read_b128 v[134:137], v130 offset:6144
	ds_read_b128 v[130:133], v130 offset:7168
	s_cmp_gt_u32 s2, 29
	s_cbranch_scc1 .LBB0_1416
	s_mul_i32 s13, s17, 0xab
	s_bfe_u32 s13, s13, 0x70009
	s_mul_i32 s13, s13, 3
	s_add_i32 s2, s4, 0x4000
	s_sub_i32 s13, s17, s13
	s_and_b32 s2, s2, 0x7c000
	s_and_b32 s13, s13, 0xff
	s_and_b32 s12, s4, 0x2000
	s_mulk_i32 s13, 0x6000
	s_lshl_b32 s2, s2, 1
	s_add_i32 s21, s11, s13
	s_setprio 1
	s_waitcnt lgkmcnt(7)
	v_mfma_f32_16x16x32_bf16 v[38:41], v[174:177], v[138:141], v[38:41]
	v_mfma_f32_16x16x32_bf16 v[122:125], v[174:177], v[142:145], v[122:125]
	v_mfma_f32_16x16x32_bf16 v[126:129], v[174:177], v[146:149], v[126:129]
	v_mfma_f32_16x16x32_bf16 v[118:121], v[174:177], v[150:153], v[118:121]
	v_lshl_add_u64 v[244:245], v[198:199], 0, s[2:3]
	s_waitcnt lgkmcnt(6)
	v_mfma_f32_16x16x32_bf16 v[26:29], v[170:173], v[138:141], v[26:29]
	s_lshl_b32 s12, s12, 1
	v_mfma_f32_16x16x32_bf16 v[110:113], v[170:173], v[142:145], v[110:113]
	s_mov_b32 s13, s3
	v_mfma_f32_16x16x32_bf16 v[114:117], v[170:173], v[146:149], v[114:117]
	v_lshl_add_u64 v[244:245], v[244:245], 0, s[12:13]
	v_mfma_f32_16x16x32_bf16 v[106:109], v[170:173], v[150:153], v[106:109]
	s_mov_b32 m0, s21
	s_waitcnt lgkmcnt(5)
	v_mfma_f32_16x16x32_bf16 v[22:25], v[166:169], v[138:141], v[22:25]
	global_load_lds_dwordx4 v[244:245], off
	v_mfma_f32_16x16x32_bf16 v[98:101], v[166:169], v[142:145], v[98:101]
	v_mfma_f32_16x16x32_bf16 v[102:105], v[166:169], v[146:149], v[102:105]
	v_lshl_add_u64 v[244:245], v[200:201], 0, s[2:3]
	v_mfma_f32_16x16x32_bf16 v[94:97], v[166:169], v[150:153], v[94:97]
	v_lshl_add_u64 v[244:245], v[244:245], 0, s[12:13]
	s_waitcnt lgkmcnt(4)
	v_mfma_f32_16x16x32_bf16 v[18:21], v[162:165], v[138:141], v[18:21]
	s_add_i32 m0, s21, 0x1000
	v_mfma_f32_16x16x32_bf16 v[86:89], v[162:165], v[142:145], v[86:89]
	global_load_lds_dwordx4 v[244:245], off
	v_mfma_f32_16x16x32_bf16 v[90:93], v[162:165], v[146:149], v[90:93]
	v_lshl_add_u64 v[244:245], v[202:203], 0, s[2:3]
	v_mfma_f32_16x16x32_bf16 v[82:85], v[162:165], v[150:153], v[82:85]
	v_lshl_add_u64 v[244:245], v[244:245], 0, s[12:13]
	s_waitcnt lgkmcnt(3)
	v_mfma_f32_16x16x32_bf16 v[14:17], v[158:161], v[138:141], v[14:17]
	v_mfma_f32_16x16x32_bf16 v[74:77], v[158:161], v[142:145], v[74:77]
	s_add_i32 m0, s21, 0x2000
	v_mfma_f32_16x16x32_bf16 v[78:81], v[158:161], v[146:149], v[78:81]
	global_load_lds_dwordx4 v[244:245], off
	v_mfma_f32_16x16x32_bf16 v[70:73], v[158:161], v[150:153], v[70:73]
	v_lshl_add_u64 v[244:245], v[204:205], 0, s[2:3]
	s_waitcnt lgkmcnt(2)
	v_mfma_f32_16x16x32_bf16 v[10:13], v[154:157], v[138:141], v[10:13]
	v_lshl_add_u64 v[244:245], v[244:245], 0, s[12:13]
	v_mfma_f32_16x16x32_bf16 v[62:65], v[154:157], v[142:145], v[62:65]
	s_add_i32 m0, s21, 0x3000
	v_mfma_f32_16x16x32_bf16 v[66:69], v[154:157], v[146:149], v[66:69]
	global_load_lds_dwordx4 v[244:245], off
	v_mfma_f32_16x16x32_bf16 v[58:61], v[154:157], v[150:153], v[58:61]
	s_waitcnt lgkmcnt(1)
	v_mfma_f32_16x16x32_bf16 v[6:9], v[134:137], v[138:141], v[6:9]
	v_lshl_add_u64 v[244:245], v[208:209], 0, s[4:5]
	v_mfma_f32_16x16x32_bf16 v[50:53], v[134:137], v[142:145], v[50:53]
	s_add_i32 m0, s21, 0x4000
	v_mfma_f32_16x16x32_bf16 v[54:57], v[134:137], v[146:149], v[54:57]
	global_load_lds_dwordx4 v[244:245], off
	v_mfma_f32_16x16x32_bf16 v[46:49], v[134:137], v[150:153], v[46:49]
	v_lshl_add_u64 v[244:245], v[206:207], 0, s[4:5]
	s_waitcnt lgkmcnt(0)
	v_mfma_f32_16x16x32_bf16 v[2:5], v[130:133], v[138:141], v[2:5]
	s_add_i32 m0, s21, 0x5000
	v_mfma_f32_16x16x32_bf16 v[34:37], v[130:133], v[142:145], v[34:37]
	global_load_lds_dwordx4 v[244:245], off
	v_mfma_f32_16x16x32_bf16 v[42:45], v[130:133], v[146:149], v[42:45]
	v_mfma_f32_16x16x32_bf16 v[30:33], v[130:133], v[150:153], v[30:33]
	s_setprio 0
	s_branch .Lgt_tail_12

; DEV float sigmoidf_(float x) { return 1.f / (1.f + __expf(-x)); }
; DEV void phase_win(const Params& P, int l, const u16* __restrict__ xb, const u16* __restrict__ Wt, u16* __restrict__ h, char* smem) {
;     ...
;     const int cb = n0 + wn * 64;
;     if (cb >= C_GL) {
;       if (cb == C_GL && l15 < 12) {
; #pragma unroll
;         for (int ms = 0; ms < 8; ++ms) {
;       asm volatile("" ::: "memory");
; #pragma unroll
;           for (int j = 0; j < 4; ++j) {
;             int row = m0 + wm * 128 + ms * 16 + quad * 4 + j;
;             gl[(size_t)row * 12 + l15] = sigmoidf_(acc[ms][0][j]);
;           }
;         }
.LBB0_2207:
	s_waitcnt vmcnt(0)
	s_movk_i32 s10, 0xc80
	v_cmp_eq_u32_e32 vcc, s10, v130
	s_and_b64 s[12:13], s[8:9], vcc
	s_and_saveexec_b64 s[10:11], s[12:13]
	s_cbranch_execz .LBB0_1399
	v_mul_f32_e32 v0, 0xbfb8aa3b, v38
	v_exp_f32_e32 v0, v0
	v_mul_f32_e32 v33, 0xbfb8aa3b, v39
	v_exp_f32_e32 v33, v33
	v_add_u32_e32 v32, s16, v178
	v_add_f32_e32 v0, 1.0, v0
	v_div_scale_f32 v30, s[12:13], v0, v0, 1.0
	v_rcp_f32_e32 v31, v30
	v_div_scale_f32 v34, vcc, 1.0, v0, 1.0
	v_add_f32_e32 v33, 1.0, v33
	v_fma_f32 v35, -v30, v31, 1.0
	v_fmac_f32_e32 v31, v35, v31
	v_mul_f32_e32 v35, v34, v31
	v_fma_f32 v36, -v30, v35, v34
	v_fmac_f32_e32 v35, v36, v31
	v_fma_f32 v30, -v30, v35, v34
	v_div_scale_f32 v34, s[12:13], v33, v33, 1.0
	v_div_fmas_f32 v30, v30, v31, v35
	v_rcp_f32_e32 v35, v34
	v_div_fixup_f32 v0, v30, v0, 1.0
	v_mad_i64_i32 v[30:31], s[12:13], v32, 48, v[188:189]
	global_store_dword v[30:31], v0, off
	v_fma_f32 v30, -v34, v35, 1.0
	v_fmac_f32_e32 v35, v30, v35
	v_div_scale_f32 v30, vcc, 1.0, v33, 1.0
	v_mul_f32_e32 v31, v30, v35
	v_fma_f32 v36, -v34, v31, v30
	v_fmac_f32_e32 v31, v36, v35
	v_fma_f32 v30, -v34, v31, v30
	v_mul_f32_e32 v34, 0xbfb8aa3b, v40
	v_exp_f32_e32 v34, v34
	v_div_fmas_f32 v30, v30, v35, v31
	v_or_b32_e32 v0, 1, v32
	v_div_fixup_f32 v33, v30, v33, 1.0
	v_add_f32_e32 v34, 1.0, v34
	v_div_scale_f32 v35, s[12:13], v34, v34, 1.0
	v_rcp_f32_e32 v36, v35
	v_mad_i64_i32 v[30:31], s[12:13], v0, 48, v[188:189]
	global_store_dword v[30:31], v33, off
	v_fma_f32 v30, -v35, v36, 1.0
	v_fmac_f32_e32 v36, v30, v36
	v_div_scale_f32 v30, vcc, 1.0, v34, 1.0
	v_mul_f32_e32 v31, v30, v36
	v_fma_f32 v33, -v35, v31, v30
	v_fmac_f32_e32 v31, v33, v36
	v_mul_f32_e32 v33, 0xbfb8aa3b, v41
	v_exp_f32_e32 v33, v33
	v_fma_f32 v30, -v35, v31, v30
	v_div_fmas_f32 v30, v30, v36, v31
	v_or_b32_e32 v0, 2, v32
	v_add_f32_e32 v33, 1.0, v33
	v_div_scale_f32 v35, s[12:13], v33, v33, 1.0
	v_rcp_f32_e32 v36, v35
	v_div_fixup_f32 v34, v30, v34, 1.0
	v_mad_i64_i32 v[30:31], s[12:13], v0, 48, v[188:189]
	global_store_dword v[30:31], v34, off
	v_fma_f32 v30, -v35, v36, 1.0
	v_fmac_f32_e32 v36, v30, v36
	v_div_scale_f32 v30, vcc, 1.0, v33, 1.0
	v_mul_f32_e32 v31, v30, v36
	v_mul_f32_e32 v26, 0xbfb8aa3b, v26
	v_or_b32_e32 v0, 3, v32
	v_fma_f32 v32, -v35, v31, v30
	v_exp_f32_e32 v26, v26
	v_fmac_f32_e32 v31, v32, v36
	v_fma_f32 v30, -v35, v31, v30
	v_div_fmas_f32 v30, v30, v36, v31
	v_div_fixup_f32 v32, v30, v33, 1.0
	v_mad_i64_i32 v[30:31], s[12:13], v0, 48, v[188:189]
	v_add_f32_e32 v0, 1.0, v26
	v_div_scale_f32 v26, s[12:13], v0, v0, 1.0
	v_rcp_f32_e32 v33, v26
	global_store_dword v[30:31], v32, off
	v_mul_f32_e32 v27, 0xbfb8aa3b, v27
	v_exp_f32_e32 v27, v27
	v_fma_f32 v31, -v26, v33, 1.0
	v_fmac_f32_e32 v33, v31, v33
	v_div_scale_f32 v31, vcc, 1.0, v0, 1.0
	v_mul_f32_e32 v32, v31, v33
	v_fma_f32 v34, -v26, v32, v31
	v_fmac_f32_e32 v32, v34, v33
	v_fma_f32 v26, -v26, v32, v31
	v_add_f32_e32 v31, 1.0, v27
	v_div_fmas_f32 v26, v26, v33, v32
	v_div_scale_f32 v32, s[12:13], v31, v31, 1.0
	v_rcp_f32_e32 v33, v32
	v_add_u32_e32 v30, s16, v184
	v_div_fixup_f32 v0, v26, v0, 1.0
	v_mad_i64_i32 v[26:27], s[12:13], v30, 48, v[188:189]
	v_mul_f32_e32 v28, 0xbfb8aa3b, v28
	global_store_dword v[26:27], v0, off
	v_fma_f32 v26, -v32, v33, 1.0
	v_exp_f32_e32 v28, v28
	v_fmac_f32_e32 v33, v26, v33
	v_div_scale_f32 v26, vcc, 1.0, v31, 1.0
	v_mul_f32_e32 v27, v26, v33
	v_fma_f32 v34, -v32, v27, v26
	v_fmac_f32_e32 v27, v34, v33
	v_add_f32_e32 v28, 1.0, v28
	v_fma_f32 v26, -v32, v27, v26
	v_div_scale_f32 v32, s[12:13], v28, v28, 1.0
	v_div_fmas_f32 v26, v26, v33, v27
	v_rcp_f32_e32 v33, v32
	v_or_b32_e32 v0, 1, v30
	v_mul_f32_e32 v29, 0xbfb8aa3b, v29
	v_div_fixup_f32 v31, v26, v31, 1.0
	v_mad_i64_i32 v[26:27], s[12:13], v0, 48, v[188:189]
	v_exp_f32_e32 v29, v29
	global_store_dword v[26:27], v31, off
	v_fma_f32 v26, -v32, v33, 1.0
	v_fmac_f32_e32 v33, v26, v33
	v_div_scale_f32 v26, vcc, 1.0, v28, 1.0
	v_mul_f32_e32 v27, v26, v33
	v_fma_f32 v31, -v32, v27, v26
	v_add_f32_e32 v29, 1.0, v29
	v_fmac_f32_e32 v27, v31, v33
	v_div_scale_f32 v31, s[12:13], v29, v29, 1.0
	v_fma_f32 v26, -v32, v27, v26
	v_rcp_f32_e32 v32, v31
	v_or_b32_e32 v0, 2, v30
	v_div_fmas_f32 v26, v26, v33, v27
	v_div_fixup_f32 v28, v26, v28, 1.0
	v_mad_i64_i32 v[26:27], s[12:13], v0, 48, v[188:189]
	global_store_dword v[26:27], v28, off
	v_fma_f32 v26, -v31, v32, 1.0
	v_fmac_f32_e32 v32, v26, v32
	v_div_scale_f32 v26, vcc, 1.0, v29, 1.0
	v_mul_f32_e32 v27, v26, v32
	v_mul_f32_e32 v22, 0xbfb8aa3b, v22
	v_fma_f32 v28, -v31, v27, v26
	v_exp_f32_e32 v22, v22
	v_fmac_f32_e32 v27, v28, v32
	v_fma_f32 v26, -v31, v27, v26
	v_or_b32_e32 v0, 3, v30
	v_div_fmas_f32 v26, v26, v32, v27
	v_div_fixup_f32 v28, v26, v29, 1.0
	v_mad_i64_i32 v[26:27], s[12:13], v0, 48, v[188:189]
	v_add_f32_e32 v0, 1.0, v22
	v_div_scale_f32 v22, s[12:13], v0, v0, 1.0
	v_rcp_f32_e32 v29, v22
	global_store_dword v[26:27], v28, off
	v_mul_f32_e32 v23, 0xbfb8aa3b, v23
	v_exp_f32_e32 v23, v23
	v_fma_f32 v27, -v22, v29, 1.0
	v_fmac_f32_e32 v29, v27, v29
	v_div_scale_f32 v27, vcc, 1.0, v0, 1.0
	v_mul_f32_e32 v28, v27, v29
	v_fma_f32 v30, -v22, v28, v27
	v_fmac_f32_e32 v28, v30, v29
	v_fma_f32 v22, -v22, v28, v27
	v_add_f32_e32 v27, 1.0, v23
	v_div_fmas_f32 v22, v22, v29, v28
	v_div_scale_f32 v28, s[12:13], v27, v27, 1.0
	v_rcp_f32_e32 v29, v28
	v_add_u32_e32 v26, s16, v234
	v_div_fixup_f32 v0, v22, v0, 1.0
	v_mad_i64_i32 v[22:23], s[12:13], v26, 48, v[188:189]
	v_mul_f32_e32 v24, 0xbfb8aa3b, v24
	global_store_dword v[22:23], v0, off
	v_fma_f32 v22, -v28, v29, 1.0
	v_exp_f32_e32 v24, v24
	v_fmac_f32_e32 v29, v22, v29
	v_div_scale_f32 v22, vcc, 1.0, v27, 1.0
; DEV float sigmoidf_(float x) { return 1.f / (1.f + __expf(-x)); }
; DEV void phase_win(const Params& P, int l, const u16* __restrict__ xb, const u16* __restrict__ Wt, u16* __restrict__ h, char* smem) {
;     ...
;           for (int j = 0; j < 4; ++j) {
;             int row = m0 + wm * 128 + ms * 16 + quad * 4 + j;
;             gl[(size_t)row * 12 + l15] = sigmoidf_(acc[ms][0][j]);
	v_mul_f32_e32 v23, v22, v29
	v_fma_f32 v30, -v28, v23, v22
	v_fmac_f32_e32 v23, v30, v29
	v_add_f32_e32 v24, 1.0, v24
	v_fma_f32 v22, -v28, v23, v22
	v_div_scale_f32 v28, s[12:13], v24, v24, 1.0
	v_div_fmas_f32 v22, v22, v29, v23
	v_rcp_f32_e32 v29, v28
	v_or_b32_e32 v0, 1, v26
	v_mul_f32_e32 v25, 0xbfb8aa3b, v25
	v_div_fixup_f32 v27, v22, v27, 1.0
	v_mad_i64_i32 v[22:23], s[12:13], v0, 48, v[188:189]
	v_exp_f32_e32 v25, v25
	global_store_dword v[22:23], v27, off
	v_fma_f32 v22, -v28, v29, 1.0
	v_fmac_f32_e32 v29, v22, v29
	v_div_scale_f32 v22, vcc, 1.0, v24, 1.0
	v_mul_f32_e32 v23, v22, v29
	v_fma_f32 v27, -v28, v23, v22
	v_add_f32_e32 v25, 1.0, v25
	v_fmac_f32_e32 v23, v27, v29
	v_div_scale_f32 v27, s[12:13], v25, v25, 1.0
	v_fma_f32 v22, -v28, v23, v22
	v_rcp_f32_e32 v28, v27
	v_or_b32_e32 v0, 2, v26
	v_div_fmas_f32 v22, v22, v29, v23
	v_div_fixup_f32 v24, v22, v24, 1.0
	v_mad_i64_i32 v[22:23], s[12:13], v0, 48, v[188:189]
	global_store_dword v[22:23], v24, off
	v_fma_f32 v22, -v27, v28, 1.0
	v_fmac_f32_e32 v28, v22, v28
	v_div_scale_f32 v22, vcc, 1.0, v25, 1.0
	v_mul_f32_e32 v23, v22, v28
	v_mul_f32_e32 v18, 0xbfb8aa3b, v18
	v_fma_f32 v24, -v27, v23, v22
	v_exp_f32_e32 v18, v18
	v_fmac_f32_e32 v23, v24, v28
	v_fma_f32 v22, -v27, v23, v22
	v_or_b32_e32 v0, 3, v26
	v_div_fmas_f32 v22, v22, v28, v23
	v_div_fixup_f32 v24, v22, v25, 1.0
	v_mad_i64_i32 v[22:23], s[12:13], v0, 48, v[188:189]
	v_add_f32_e32 v0, 1.0, v18
	v_div_scale_f32 v18, s[12:13], v0, v0, 1.0
	v_rcp_f32_e32 v25, v18
	global_store_dword v[22:23], v24, off
	v_mul_f32_e32 v19, 0xbfb8aa3b, v19
	v_exp_f32_e32 v19, v19
	v_fma_f32 v23, -v18, v25, 1.0
	v_fmac_f32_e32 v25, v23, v25
	v_div_scale_f32 v23, vcc, 1.0, v0, 1.0
	v_mul_f32_e32 v24, v23, v25
	v_fma_f32 v26, -v18, v24, v23
	v_fmac_f32_e32 v24, v26, v25
	v_fma_f32 v18, -v18, v24, v23
	v_add_f32_e32 v23, 1.0, v19
	v_div_fmas_f32 v18, v18, v25, v24
	v_div_scale_f32 v24, s[12:13], v23, v23, 1.0
	v_rcp_f32_e32 v25, v24
	v_add_u32_e32 v22, s16, v235
	v_div_fixup_f32 v0, v18, v0, 1.0
	v_mad_i64_i32 v[18:19], s[12:13], v22, 48, v[188:189]
	v_mul_f32_e32 v20, 0xbfb8aa3b, v20
	global_store_dword v[18:19], v0, off
	v_fma_f32 v18, -v24, v25, 1.0
	v_exp_f32_e32 v20, v20
	v_fmac_f32_e32 v25, v18, v25
	v_div_scale_f32 v18, vcc, 1.0, v23, 1.0
	v_mul_f32_e32 v19, v18, v25
	v_fma_f32 v26, -v24, v19, v18
	v_fmac_f32_e32 v19, v26, v25
	v_add_f32_e32 v20, 1.0, v20
	v_fma_f32 v18, -v24, v19, v18
	v_div_scale_f32 v24, s[12:13], v20, v20, 1.0
	v_div_fmas_f32 v18, v18, v25, v19
	v_rcp_f32_e32 v25, v24
	v_or_b32_e32 v0, 1, v22
	v_mul_f32_e32 v21, 0xbfb8aa3b, v21
	v_div_fixup_f32 v23, v18, v23, 1.0
	v_mad_i64_i32 v[18:19], s[12:13], v0, 48, v[188:189]
	v_exp_f32_e32 v21, v21
	global_store_dword v[18:19], v23, off
	v_fma_f32 v18, -v24, v25, 1.0
	v_fmac_f32_e32 v25, v18, v25
	v_div_scale_f32 v18, vcc, 1.0, v20, 1.0
	v_mul_f32_e32 v19, v18, v25
	v_fma_f32 v23, -v24, v19, v18
	v_add_f32_e32 v21, 1.0, v21
	v_fmac_f32_e32 v19, v23, v25
	v_div_scale_f32 v23, s[12:13], v21, v21, 1.0
	v_fma_f32 v18, -v24, v19, v18
	v_rcp_f32_e32 v24, v23
	v_or_b32_e32 v0, 2, v22
	v_div_fmas_f32 v18, v18, v25, v19
	v_div_fixup_f32 v20, v18, v20, 1.0
	v_mad_i64_i32 v[18:19], s[12:13], v0, 48, v[188:189]
	global_store_dword v[18:19], v20, off
	v_fma_f32 v18, -v23, v24, 1.0
	v_fmac_f32_e32 v24, v18, v24
	v_div_scale_f32 v18, vcc, 1.0, v21, 1.0
	v_mul_f32_e32 v19, v18, v24
	v_mul_f32_e32 v14, 0xbfb8aa3b, v14
	v_fma_f32 v20, -v23, v19, v18
	v_exp_f32_e32 v14, v14
	v_fmac_f32_e32 v19, v20, v24
	v_fma_f32 v18, -v23, v19, v18
	v_or_b32_e32 v0, 3, v22
	v_div_fmas_f32 v18, v18, v24, v19
	v_div_fixup_f32 v20, v18, v21, 1.0
	v_mad_i64_i32 v[18:19], s[12:13], v0, 48, v[188:189]
	v_add_f32_e32 v0, 1.0, v14
	v_div_scale_f32 v14, s[12:13], v0, v0, 1.0
	v_rcp_f32_e32 v21, v14
	global_store_dword v[18:19], v20, off
	v_mul_f32_e32 v15, 0xbfb8aa3b, v15
	v_exp_f32_e32 v15, v15
	v_fma_f32 v19, -v14, v21, 1.0
	v_fmac_f32_e32 v21, v19, v21
	v_div_scale_f32 v19, vcc, 1.0, v0, 1.0
	v_mul_f32_e32 v20, v19, v21
	v_fma_f32 v22, -v14, v20, v19
	v_fmac_f32_e32 v20, v22, v21
	v_fma_f32 v14, -v14, v20, v19
	v_add_f32_e32 v19, 1.0, v15
	v_div_fmas_f32 v14, v14, v21, v20
	v_div_scale_f32 v20, s[12:13], v19, v19, 1.0
	v_rcp_f32_e32 v21, v20
	v_add_u32_e32 v18, s16, v236
	v_div_fixup_f32 v0, v14, v0, 1.0
	v_mad_i64_i32 v[14:15], s[12:13], v18, 48, v[188:189]
	v_mul_f32_e32 v16, 0xbfb8aa3b, v16
	global_store_dword v[14:15], v0, off
	v_fma_f32 v14, -v20, v21, 1.0
	v_exp_f32_e32 v16, v16
	v_fmac_f32_e32 v21, v14, v21
	v_div_scale_f32 v14, vcc, 1.0, v19, 1.0
	v_mul_f32_e32 v15, v14, v21
	v_fma_f32 v22, -v20, v15, v14
	v_fmac_f32_e32 v15, v22, v21
	v_add_f32_e32 v16, 1.0, v16
	v_fma_f32 v14, -v20, v15, v14
	v_div_scale_f32 v20, s[12:13], v16, v16, 1.0
	v_div_fmas_f32 v14, v14, v21, v15
	v_rcp_f32_e32 v21, v20
	v_or_b32_e32 v0, 1, v18
	v_mul_f32_e32 v17, 0xbfb8aa3b, v17
	v_div_fixup_f32 v19, v14, v19, 1.0
	v_mad_i64_i32 v[14:15], s[12:13], v0, 48, v[188:189]
	v_exp_f32_e32 v17, v17
	global_store_dword v[14:15], v19, off
	v_fma_f32 v14, -v20, v21, 1.0
	v_fmac_f32_e32 v21, v14, v21
	v_div_scale_f32 v14, vcc, 1.0, v16, 1.0
	v_mul_f32_e32 v15, v14, v21
	v_fma_f32 v19, -v20, v15, v14
	v_add_f32_e32 v17, 1.0, v17
	v_fmac_f32_e32 v15, v19, v21
	v_div_scale_f32 v19, s[12:13], v17, v17, 1.0
	v_fma_f32 v14, -v20, v15, v14
	v_rcp_f32_e32 v20, v19
	v_or_b32_e32 v0, 2, v18
	v_div_fmas_f32 v14, v14, v21, v15
	v_div_fixup_f32 v16, v14, v16, 1.0
	v_mad_i64_i32 v[14:15], s[12:13], v0, 48, v[188:189]
	global_store_dword v[14:15], v16, off
	v_fma_f32 v14, -v19, v20, 1.0
	v_fmac_f32_e32 v20, v14, v20
	v_div_scale_f32 v14, vcc, 1.0, v17, 1.0
; DEV float sigmoidf_(float x) { return 1.f / (1.f + __expf(-x)); }
; DEV void phase_win(const Params& P, int l, const u16* __restrict__ xb, const u16* __restrict__ Wt, u16* __restrict__ h, char* smem) {
;     ...
;           for (int j = 0; j < 4; ++j) {
;             int row = m0 + wm * 128 + ms * 16 + quad * 4 + j;
;             gl[(size_t)row * 12 + l15] = sigmoidf_(acc[ms][0][j]);
	v_mul_f32_e32 v15, v14, v20
	v_mul_f32_e32 v10, 0xbfb8aa3b, v10
	v_fma_f32 v16, -v19, v15, v14
	v_exp_f32_e32 v10, v10
	v_fmac_f32_e32 v15, v16, v20
	v_fma_f32 v14, -v19, v15, v14
	v_or_b32_e32 v0, 3, v18
	v_div_fmas_f32 v14, v14, v20, v15
	v_div_fixup_f32 v16, v14, v17, 1.0
	v_mad_i64_i32 v[14:15], s[12:13], v0, 48, v[188:189]
	v_add_f32_e32 v0, 1.0, v10
	v_div_scale_f32 v10, s[12:13], v0, v0, 1.0
	v_rcp_f32_e32 v17, v10
	global_store_dword v[14:15], v16, off
	v_mul_f32_e32 v11, 0xbfb8aa3b, v11
	v_exp_f32_e32 v11, v11
	v_fma_f32 v15, -v10, v17, 1.0
	v_fmac_f32_e32 v17, v15, v17
	v_div_scale_f32 v15, vcc, 1.0, v0, 1.0
	v_mul_f32_e32 v16, v15, v17
	v_fma_f32 v18, -v10, v16, v15
	v_fmac_f32_e32 v16, v18, v17
	v_fma_f32 v10, -v10, v16, v15
	v_add_f32_e32 v15, 1.0, v11
	v_div_fmas_f32 v10, v10, v17, v16
	v_div_scale_f32 v16, s[12:13], v15, v15, 1.0
	v_rcp_f32_e32 v17, v16
	v_add_u32_e32 v14, s16, v237
	v_div_fixup_f32 v0, v10, v0, 1.0
	v_mad_i64_i32 v[10:11], s[12:13], v14, 48, v[188:189]
	v_mul_f32_e32 v12, 0xbfb8aa3b, v12
	global_store_dword v[10:11], v0, off
	v_fma_f32 v10, -v16, v17, 1.0
	v_exp_f32_e32 v12, v12
	v_fmac_f32_e32 v17, v10, v17
	v_div_scale_f32 v10, vcc, 1.0, v15, 1.0
	v_mul_f32_e32 v11, v10, v17
	v_fma_f32 v18, -v16, v11, v10
	v_fmac_f32_e32 v11, v18, v17
	v_add_f32_e32 v12, 1.0, v12
	v_fma_f32 v10, -v16, v11, v10
	v_div_scale_f32 v16, s[12:13], v12, v12, 1.0
	v_div_fmas_f32 v10, v10, v17, v11
	v_rcp_f32_e32 v17, v16
	v_or_b32_e32 v0, 1, v14
	v_mul_f32_e32 v13, 0xbfb8aa3b, v13
	v_div_fixup_f32 v15, v10, v15, 1.0
	v_mad_i64_i32 v[10:11], s[12:13], v0, 48, v[188:189]
	v_exp_f32_e32 v13, v13
	global_store_dword v[10:11], v15, off
	v_fma_f32 v10, -v16, v17, 1.0
	v_fmac_f32_e32 v17, v10, v17
	v_div_scale_f32 v10, vcc, 1.0, v12, 1.0
	v_mul_f32_e32 v11, v10, v17
	v_fma_f32 v15, -v16, v11, v10
	v_add_f32_e32 v13, 1.0, v13
	v_fmac_f32_e32 v11, v15, v17
	v_div_scale_f32 v15, s[12:13], v13, v13, 1.0
	v_fma_f32 v10, -v16, v11, v10
	v_rcp_f32_e32 v16, v15
	v_or_b32_e32 v0, 2, v14
	v_div_fmas_f32 v10, v10, v17, v11
	v_div_fixup_f32 v12, v10, v12, 1.0
	v_mad_i64_i32 v[10:11], s[12:13], v0, 48, v[188:189]
	global_store_dword v[10:11], v12, off
	v_fma_f32 v10, -v15, v16, 1.0
	v_fmac_f32_e32 v16, v10, v16
	v_div_scale_f32 v10, vcc, 1.0, v13, 1.0
	v_mul_f32_e32 v11, v10, v16
	v_mul_f32_e32 v6, 0xbfb8aa3b, v6
	v_fma_f32 v12, -v15, v11, v10
	v_exp_f32_e32 v6, v6
	v_fmac_f32_e32 v11, v12, v16
	v_fma_f32 v10, -v15, v11, v10
	v_or_b32_e32 v0, 3, v14
	v_div_fmas_f32 v10, v10, v16, v11
	v_div_fixup_f32 v12, v10, v13, 1.0
	v_mad_i64_i32 v[10:11], s[12:13], v0, 48, v[188:189]
	v_add_f32_e32 v0, 1.0, v6
	v_div_scale_f32 v6, s[12:13], v0, v0, 1.0
	v_rcp_f32_e32 v13, v6
	global_store_dword v[10:11], v12, off
	v_mul_f32_e32 v7, 0xbfb8aa3b, v7
	v_exp_f32_e32 v7, v7
	v_fma_f32 v11, -v6, v13, 1.0
	v_fmac_f32_e32 v13, v11, v13
	v_div_scale_f32 v11, vcc, 1.0, v0, 1.0
	v_mul_f32_e32 v12, v11, v13
	v_fma_f32 v14, -v6, v12, v11
	v_fmac_f32_e32 v12, v14, v13
	v_fma_f32 v6, -v6, v12, v11
	v_add_f32_e32 v11, 1.0, v7
	v_div_fmas_f32 v6, v6, v13, v12
	v_div_scale_f32 v12, s[12:13], v11, v11, 1.0
	v_rcp_f32_e32 v13, v12
	v_add_u32_e32 v10, s16, v238
	v_div_fixup_f32 v0, v6, v0, 1.0
	v_mad_i64_i32 v[6:7], s[12:13], v10, 48, v[188:189]
	v_mul_f32_e32 v8, 0xbfb8aa3b, v8
	global_store_dword v[6:7], v0, off
	v_fma_f32 v6, -v12, v13, 1.0
	v_exp_f32_e32 v8, v8
	v_fmac_f32_e32 v13, v6, v13
	v_div_scale_f32 v6, vcc, 1.0, v11, 1.0
	v_mul_f32_e32 v7, v6, v13
	v_fma_f32 v14, -v12, v7, v6
	v_fmac_f32_e32 v7, v14, v13
	v_add_f32_e32 v8, 1.0, v8
	v_fma_f32 v6, -v12, v7, v6
	v_div_scale_f32 v12, s[12:13], v8, v8, 1.0
	v_div_fmas_f32 v6, v6, v13, v7
	v_rcp_f32_e32 v13, v12
	v_or_b32_e32 v0, 1, v10
	v_mul_f32_e32 v9, 0xbfb8aa3b, v9
	v_div_fixup_f32 v11, v6, v11, 1.0
	v_mad_i64_i32 v[6:7], s[12:13], v0, 48, v[188:189]
	v_exp_f32_e32 v9, v9
	global_store_dword v[6:7], v11, off
	v_fma_f32 v6, -v12, v13, 1.0
	v_fmac_f32_e32 v13, v6, v13
	v_div_scale_f32 v6, vcc, 1.0, v8, 1.0
	v_mul_f32_e32 v7, v6, v13
	v_fma_f32 v11, -v12, v7, v6
	v_add_f32_e32 v9, 1.0, v9
	v_fmac_f32_e32 v7, v11, v13
	v_div_scale_f32 v11, s[12:13], v9, v9, 1.0
	v_fma_f32 v6, -v12, v7, v6
	v_rcp_f32_e32 v12, v11
	v_or_b32_e32 v0, 2, v10
	v_div_fmas_f32 v6, v6, v13, v7
	v_div_fixup_f32 v8, v6, v8, 1.0
	v_mad_i64_i32 v[6:7], s[12:13], v0, 48, v[188:189]
	global_store_dword v[6:7], v8, off
	v_fma_f32 v6, -v11, v12, 1.0
	v_fmac_f32_e32 v12, v6, v12
	v_div_scale_f32 v6, vcc, 1.0, v9, 1.0
	v_mul_f32_e32 v7, v6, v12
	v_mul_f32_e32 v2, 0xbfb8aa3b, v2
	v_fma_f32 v8, -v11, v7, v6
	v_exp_f32_e32 v2, v2
	v_fmac_f32_e32 v7, v8, v12
	v_fma_f32 v6, -v11, v7, v6
	v_or_b32_e32 v0, 3, v10
	v_div_fmas_f32 v6, v6, v12, v7
	v_div_fixup_f32 v8, v6, v9, 1.0
	v_mad_i64_i32 v[6:7], s[12:13], v0, 48, v[188:189]
	v_add_f32_e32 v0, 1.0, v2
	v_div_scale_f32 v2, s[12:13], v0, v0, 1.0
	v_rcp_f32_e32 v9, v2
	global_store_dword v[6:7], v8, off
	v_mul_f32_e32 v3, 0xbfb8aa3b, v3
	v_exp_f32_e32 v3, v3
	v_fma_f32 v7, -v2, v9, 1.0
	v_fmac_f32_e32 v9, v7, v9
	v_div_scale_f32 v7, vcc, 1.0, v0, 1.0
	v_mul_f32_e32 v8, v7, v9
	v_fma_f32 v10, -v2, v8, v7
	v_fmac_f32_e32 v8, v10, v9
	v_fma_f32 v2, -v2, v8, v7
	v_add_f32_e32 v7, 1.0, v3
	v_div_fmas_f32 v2, v2, v9, v8
	v_div_scale_f32 v8, s[12:13], v7, v7, 1.0
	v_rcp_f32_e32 v9, v8
	v_add_u32_e32 v6, s16, v239
	v_div_fixup_f32 v0, v2, v0, 1.0
	v_mad_i64_i32 v[2:3], s[12:13], v6, 48, v[188:189]
	v_mul_f32_e32 v4, 0xbfb8aa3b, v4
	global_store_dword v[2:3], v0, off
	v_fma_f32 v2, -v8, v9, 1.0
	v_exp_f32_e32 v4, v4
	v_fmac_f32_e32 v9, v2, v9
	v_div_scale_f32 v2, vcc, 1.0, v7, 1.0
	v_mul_f32_e32 v3, v2, v9
	v_fma_f32 v10, -v8, v3, v2
	v_fmac_f32_e32 v3, v10, v9
	v_add_f32_e32 v4, 1.0, v4
	v_fma_f32 v2, -v8, v3, v2
	v_div_scale_f32 v8, s[12:13], v4, v4, 1.0
	v_div_fmas_f32 v2, v2, v9, v3
	v_rcp_f32_e32 v9, v8
	v_or_b32_e32 v0, 1, v6
	v_mul_f32_e32 v5, 0xbfb8aa3b, v5
	v_div_fixup_f32 v7, v2, v7, 1.0
	v_mad_i64_i32 v[2:3], s[12:13], v0, 48, v[188:189]
	v_exp_f32_e32 v5, v5
	global_store_dword v[2:3], v7, off
	v_fma_f32 v2, -v8, v9, 1.0
	v_fmac_f32_e32 v9, v2, v9
	v_div_scale_f32 v2, vcc, 1.0, v4, 1.0
	v_mul_f32_e32 v3, v2, v9
	v_fma_f32 v7, -v8, v3, v2
	v_add_f32_e32 v5, 1.0, v5
	v_fmac_f32_e32 v3, v7, v9
	v_div_scale_f32 v7, s[12:13], v5, v5, 1.0
	v_fma_f32 v2, -v8, v3, v2
	v_rcp_f32_e32 v8, v7
	v_or_b32_e32 v0, 2, v6
	v_div_fmas_f32 v2, v2, v9, v3
	v_div_fixup_f32 v4, v2, v4, 1.0
	v_mad_i64_i32 v[2:3], s[12:13], v0, 48, v[188:189]
	global_store_dword v[2:3], v4, off
	v_fma_f32 v2, -v7, v8, 1.0
	v_fmac_f32_e32 v8, v2, v8
	v_div_scale_f32 v2, vcc, 1.0, v5, 1.0
	v_mul_f32_e32 v3, v2, v8
	v_fma_f32 v4, -v7, v3, v2
	v_fmac_f32_e32 v3, v4, v8
	v_fma_f32 v2, -v7, v3, v2
	v_or_b32_e32 v0, 3, v6
	v_div_fmas_f32 v2, v2, v8, v3
	v_div_fixup_f32 v4, v2, v5, 1.0
	v_mad_i64_i32 v[2:3], s[12:13], v0, 48, v[188:189]
	global_store_dword v[2:3], v4, off
	s_branch .LBB0_1399
